# MLA attention K loop: K/V staging addresses hoisted out of the loop (persistent lane addresses + per-lane stride, V via SGPR base), on top of v24
# speedup vs baseline: 1.0071x; 1.0053x over previous
; DI int tid_opaque() { int t = threadIdx.x; asm volatile("" : "+v"(t)); return t; }
; template <int DK, int DV, int MODE>
; DI void att_gload(const AttArgs& a, int tile, u32x4 (&kr)[(64 * (DK / 8) + NT - 1) / NT], u32x4 (&vr)[(64 * (DV / 8) + NT - 1) / NT]) {
;   constexpr int CK = DK / 8, CV = DV / 8;
;   constexpr int NKL = (64 * CK + NT - 1) / NT, NVL = (64 * CV + NT - 1) / NT;
;   const int t = tid_opaque();
;   const int kbase = tile * 64;
; #pragma unroll
;   for (int i = 0; i < NKL; ++i) {
;     const int id = min(t + NT * i, 64 * CK - 1);
;     const int row = id / CK, c = id % CK;
;     if constexpr (MODE == 3) {
;       const bf16_t* src = (c < 8) ? (a.k + (size_t)(kbase + row) * a.ldk + c * 8) : (a.k2 + (size_t)(kbase + row) * a.ldk2 + (c - 8) * 8);
;       kr[i] = *(const u32x4*)src;
;     } else {
;       kr[i] = *(const u32x4*)(a.k + (size_t)(kbase + row) * a.ldk + c * 8);
;     }
;   }
; #pragma unroll
;   for (int i = 0; i < NVL; ++i) {
;     const int id = t + NT * i;
;     const int row = id / CV, c = id % CV;
;     vr[i] = *(const u32x4*)(a.v + (size_t)(kbase + row) * a.ldv + c * 8);
;   }
; }
; template <int DK, int DV>
; DI void att_swrite(int buf, const u32x4 (&kr)[(64 * (DK / 8) + NT - 1) / NT], const u32x4 (&vr)[(64 * (DV / 8) + NT - 1) / NT]) {
;   constexpr int CK = DK / 8, CV = DV / 8;
;   constexpr int KST = DK * 2 + 16, VST = DV * 2 + 16;
;   constexpr int KBYTES = 64 * KST, VBYTES = 64 * VST, BUFB = KBYTES + VBYTES;
;   constexpr int NKL = (64 * CK + NT - 1) / NT, NVL = (64 * CV + NT - 1) / NT;
;   const int t = tid_opaque();
; #pragma unroll
;   for (int i = 0; i < NKL; ++i) {
;     const int id = t + NT * i;
;     const int row = id / CK, c = id % CK;
;     if (id < 64 * CK) *(u32x4*)(smem + buf * BUFB + row * KST + c * 16) = kr[i];
;   }
; #pragma unroll
;   for (int i = 0; i < NVL; ++i) {
;     const int id = t + NT * i;
;     const int row = id / CV, c = id % CV;
;     *(u32x4*)(smem + buf * BUFB + KBYTES + row * VST + c * 16) = vr[i];
;   }
.LBB0_765:
	s_or_b64 exec, exec, s[6:7]
	v_ashrrev_i32_e32 v1, 31, v0
	v_lshrrev_b32_e32 v1, 29, v1
	v_add_u32_e32 v1, v0, v1
	s_waitcnt vmcnt(2)
	v_lshrrev_b32_e32 v4, 3, v1
	v_and_b32_e32 v1, 0xffffff8, v1
	s_movk_i32 s6, 0x90
	v_sub_u32_e32 v0, v0, v1
	v_mul_lo_u32 v1, v4, s6
	v_lshl_add_u32 v0, v0, 4, v1
	s_waitcnt vmcnt(1)
	v_mov_b32_e32 v8, v224
	s_waitcnt vmcnt(0)
	ds_write_b128 v0, v[12:15] offset:13312
	s_mov_b32 s6, 0x2aaaaaab
	v_min_i32_e32 v0, 0x2ff, v8
	v_mul_hi_i32 v1, v0, s6
	v_lshrrev_b32_e32 v4, 31, v1
	v_ashrrev_i32_e32 v1, 1, v1
	v_add_u32_e32 v1, v1, v4
	v_mul_lo_u32 v4, v1, 12
	v_sub_u32_e32 v0, v0, v4
	v_add_u32_e32 v6, 64, v1
	v_cmp_lt_i32_e32 vcc, 7, v0
	v_ashrrev_i32_e32 v7, 31, v6
	v_lshlrev_b32_e32 v0, 3, v0
	s_and_saveexec_b64 s[6:7], vcc
	s_xor_b64 s[6:7], exec, s[6:7]
	v_lshlrev_b64 v[4:5], 12, v[6:7]
	v_lshl_add_u64 v[4:5], s[30:31], 0, v[4:5]
	v_mov_b32_e32 v1, v2
	v_lshl_add_u64 v[0:1], v[0:1], 1, v[4:5]
	s_mov_b64 s[8:9], 0x280
	v_lshl_add_u64 v[4:5], v[0:1], 0, s[8:9]
	s_andn2_saveexec_b64 s[6:7], s[6:7]
	v_lshlrev_b64 v[4:5], 11, v[6:7]
	v_lshl_add_u64 v[4:5], s[0:1], 0, v[4:5]
	v_ashrrev_i32_e32 v1, 31, v0
	v_lshl_add_u64 v[4:5], v[0:1], 1, v[4:5]
	s_or_b64 exec, exec, s[6:7]
	global_load_dwordx4 v[192:195], v[4:5], off
	v_mov_b32_e32 v226, v4
	v_mov_b32_e32 v227, v5
	v_mov_b32_e32 v236, 0x20000
	v_mov_b32_e32 v237, 0x40000
	v_cndmask_b32_e32 v236, v236, v237, vcc
	v_min_i32_e32 v0, 0xff, v8
	v_add_u32_e32 v0, 0x200, v0
	s_mov_b32 s6, 0x2aaaaaab
	v_mul_hi_i32 v1, v0, s6
	v_lshrrev_b32_e32 v4, 31, v1
	v_ashrrev_i32_e32 v1, 1, v1
	v_add_u32_e32 v1, v1, v4
	v_mul_lo_u32 v4, v1, 12
	v_sub_u32_e32 v0, v0, v4
	v_add_u32_e32 v6, 64, v1
	v_cmp_lt_i32_e32 vcc, 7, v0
	v_ashrrev_i32_e32 v7, 31, v6
	v_lshlrev_b32_e32 v4, 3, v0
	s_and_saveexec_b64 s[6:7], vcc
	s_xor_b64 s[6:7], exec, s[6:7]
	v_lshlrev_b64 v[0:1], 12, v[6:7]
	v_lshl_add_u64 v[0:1], s[30:31], 0, v[0:1]
	v_mov_b32_e32 v5, v2
	v_lshl_add_u64 v[0:1], v[4:5], 1, v[0:1]
	s_mov_b64 s[8:9], 0x280
	v_lshl_add_u64 v[0:1], v[0:1], 0, s[8:9]
	s_andn2_saveexec_b64 s[6:7], s[6:7]
	v_lshlrev_b64 v[0:1], 11, v[6:7]
	v_lshl_add_u64 v[0:1], s[0:1], 0, v[0:1]
	v_ashrrev_i32_e32 v5, 31, v4
	v_lshl_add_u64 v[0:1], v[4:5], 1, v[0:1]
	s_or_b64 exec, exec, s[6:7]
	global_load_dwordx4 v[196:199], v[0:1], off
	v_mov_b32_e32 v228, v0
	v_mov_b32_e32 v229, v1
	v_mov_b32_e32 v237, 0x20000
	v_mov_b32_e32 v0, 0x40000
	v_cndmask_b32_e32 v237, v237, v0, vcc
	v_ashrrev_i32_e32 v0, 31, v8
	v_lshrrev_b32_e32 v0, 29, v0
	v_add_u32_e32 v1, v8, v0
	v_ashrrev_i32_e32 v0, 3, v1
	v_and_b32_e32 v1, 0x1ffffff8, v1
	v_sub_u32_e32 v4, v8, v1
	v_ashrrev_i32_e32 v1, 31, v0
	v_lshlrev_b64 v[0:1], 11, v[0:1]
	v_lshlrev_b32_e32 v4, 3, v4
	v_ashrrev_i32_e32 v5, 31, v4
	v_lshl_add_u64 v[0:1], s[2:3], 0, v[0:1]
	v_lshl_add_u64 v[0:1], v[4:5], 1, v[0:1]
	s_mov_b32 s6, 0x20000
	v_add_co_u32_e32 v0, vcc, s6, v0
	v_lshlrev_b32_e32 v4, 2, v16
	s_nop 0
	v_addc_co_u32_e32 v1, vcc, 0, v1, vcc
	global_load_dwordx4 v[200:203], v[0:1], off
	v_bfe_u32 v0, v16, 2, 2
	v_and_b32_e32 v1, 16, v16
	v_lshl_or_b32 v0, v17, 2, v0
	v_and_or_b32 v1, v4, 12, v1
	v_mov_b32_e32 v14, v2
	v_mov_b32_e32 v15, v2
	v_lshlrev_b32_e32 v209, 3, v17
	v_lshlrev_b32_e32 v238, 1, v1
	v_mul_u32_u24_e32 v242, 0xd0, v3
	v_mul_u32_u24_e32 v239, 0x90, v0
	v_mov_b32_e32 v0, v2
	v_mov_b32_e32 v1, v2
	v_mov_b32_e32 v3, v2
	v_mov_b32_e32 v4, v2
	v_mov_b32_e32 v5, v2
	v_mov_b32_e32 v6, v2
	v_mov_b32_e32 v7, v2
	v_mov_b32_e32 v8, v2
	v_mov_b32_e32 v9, v2
	v_mov_b32_e32 v10, v2
	v_mov_b32_e32 v11, v2
	v_mov_b32_e32 v12, v2
	v_mov_b32_e32 v13, v2
	v_mov_b64_e32 v[30:31], v[14:15]
	v_mov_b64_e32 v[46:47], v[14:15]
	v_mov_b64_e32 v[62:63], v[14:15]
	v_mov_b64_e32 v[78:79], v[14:15]
	v_ashrrev_i32_e32 v207, 31, v206
	v_ashrrev_i32_e32 v205, 31, v204
	s_mov_b32 s14, 0
	v_mov_b32_e32 v240, 0
	v_mov_b32_e32 v211, 0xf149f2ca
	s_add_u32 s6, s2, 0x40000
	s_addc_u32 s7, s3, 0
	v_mov_b64_e32 v[28:29], v[12:13]
	v_mov_b64_e32 v[26:27], v[10:11]
	v_mov_b64_e32 v[24:25], v[8:9]
	v_mov_b64_e32 v[22:23], v[6:7]
	v_mov_b64_e32 v[20:21], v[4:5]
	v_mov_b64_e32 v[18:19], v[2:3]
	v_mov_b64_e32 v[16:17], v[0:1]
	v_mov_b64_e32 v[44:45], v[12:13]
	v_mov_b64_e32 v[42:43], v[10:11]
	v_mov_b64_e32 v[40:41], v[8:9]
	v_mov_b64_e32 v[38:39], v[6:7]
	v_mov_b64_e32 v[36:37], v[4:5]
	v_mov_b64_e32 v[34:35], v[2:3]
	v_mov_b64_e32 v[32:33], v[0:1]
	v_mov_b64_e32 v[60:61], v[12:13]
	v_mov_b64_e32 v[58:59], v[10:11]
	v_mov_b64_e32 v[56:57], v[8:9]
	v_mov_b64_e32 v[54:55], v[6:7]
	v_mov_b64_e32 v[52:53], v[4:5]
	v_mov_b64_e32 v[50:51], v[2:3]
	v_mov_b64_e32 v[48:49], v[0:1]
	v_mov_b64_e32 v[76:77], v[12:13]
	v_mov_b64_e32 v[74:75], v[10:11]
	v_mov_b64_e32 v[72:73], v[8:9]
	v_mov_b64_e32 v[70:71], v[6:7]
	v_mov_b64_e32 v[68:69], v[4:5]
	v_mov_b64_e32 v[66:67], v[2:3]
	v_mov_b64_e32 v[64:65], v[0:1]
	v_mov_b32_e32 v243, 0xf149f2ca
	v_mov_b32_e32 v241, 0
	s_mov_b32 s8, 0x2aaaaaab
	v_mul_hi_i32 v0, v224, s8
	v_ashrrev_i32_e32 v0, 1, v0
	v_mul_lo_u32 v1, v0, 12
	v_sub_u32_e32 v1, v224, v1
	v_mul_u32_u24_e32 v0, 0xd0, v0
	v_lshl_add_u32 v248, v1, 4, v0
	v_add_u32_e32 v3, 0x200, v224
	v_mul_hi_i32 v0, v3, s8
	v_ashrrev_i32_e32 v0, 1, v0
	v_mul_lo_u32 v1, v0, 12
	v_sub_u32_e32 v1, v3, v1
	v_mul_u32_u24_e32 v0, 0xd0, v0
	v_lshl_add_u32 v249, v1, 4, v0
	v_lshrrev_b32_e32 v0, 3, v224
	v_and_b32_e32 v1, 7, v224
	v_mul_u32_u24_e32 v3, 0x90, v0
	v_lshl_add_u32 v250, v1, 4, v3
	v_lshlrev_b32_e32 v0, 11, v0
	v_lshl_or_b32 v251, v1, 4, v0
	s_movk_i32 s8, 0x100
	v_cmp_gt_i32_e64 s[100:101], s8, v224
	s_waitcnt lgkmcnt(0)
	s_barrier
	s_branch .LBB0_775
; DI float fexp2(float x) { return __builtin_amdgcn_exp2f(x); }
; template <int DK, int DV, int MODE, int QB, bool PACK = false>
; DI void attn_item(const AttArgs& a, int q0, int t_lo, int t_hi) {
;     ...
;         const float mc = -m[qb] * cexp;
;         const f32x2 c2 = {cexp, cexp}, mc2 = {mc, mc};
;         f32x2 ps2 = {0.f, 0.f};
; #pragma unroll
;         for (int kb = 0; kb < 2; ++kb)
; #pragma unroll
;           for (int i = 0; i < 16; i += 2) {
;             const f32x2 sv = {s[qb][kb][i], s[qb][kb][i + 1]};
;             const f32x2 e2 = sv * c2 + mc2;
;             f32x2 pv = {fexp2(e2[0]), fexp2(e2[1])};
;             if constexpr (MODE == 1 || MODE == 2) {
;               pv[0] = (sv[0] > -1e29f) ? pv[0] : 0.f;
;               pv[1] = (sv[1] > -1e29f) ? pv[1] : 0.f;
;             }
;             s[qb][kb][i] = pv[0];
;             s[qb][kb][i + 1] = pv[1];
;             ps2 += pv;
;           }
;         lsum[qb] += ps2[0] + ps2[1];
;       }
; #pragma unroll
;       for (int qb = 0; qb < QB; ++qb)
; #pragma unroll
;         for (int kb = 0; kb < 2; ++kb)
; #pragma unroll
;           for (int st = 0; st < 2; ++st) {
;             u32x4 pk;
;             pk[0] = pack2(s[qb][kb][8 * st + 0], s[qb][kb][8 * st + 1]);
;             pk[1] = pack2(s[qb][kb][8 * st + 2], s[qb][kb][8 * st + 3]);
;             pk[2] = pack2(s[qb][kb][8 * st + 4], s[qb][kb][8 * st + 5]);
;             pk[3] = pack2(s[qb][kb][8 * st + 6], s[qb][kb][8 * st + 7]);
;             const bf16x8 pf = __builtin_bit_cast(bf16x8, pk);
;             const unsigned char* vrow = Vb + (kb * 32 + 16 * st + 4 * h + vq) * VST + (16 * vblk + 4 * vp) * 2;
; #pragma unroll
;             for (int d = 0; d < NDB; ++d) {
;               s16x4 lo = __builtin_amdgcn_ds_read_tr16_b64_v4i16((s16x4 __attribute__((address_space(3)))*)(vrow + d * 64));
;               s16x4 hi = __builtin_amdgcn_ds_read_tr16_b64_v4i16((s16x4 __attribute__((address_space(3)))*)(vrow + 8 * VST + d * 64));
.LBB0_774:
	v_mul_f32_e32 v0, 0xbe16c740, v243
	v_pk_fma_f32 v[4:5], v[128:129], s[28:29], v[0:1] op_sel_hi:[1,0,0]
	v_pk_fma_f32 v[6:7], v[130:131], s[28:29], v[0:1] op_sel_hi:[1,0,0]
	v_exp_f32_e32 v4, v4
	v_exp_f32_e32 v5, v5
	v_exp_f32_e32 v6, v6
	v_exp_f32_e32 v7, v7
	v_pk_fma_f32 v[14:15], v[136:137], s[28:29], v[0:1] op_sel_hi:[1,0,0]
	v_pk_add_f32 v[8:9], v[4:5], 0 op_sel_hi:[1,0]
	v_exp_f32_e32 v216, v14
	v_pk_add_f32 v[10:11], v[6:7], v[8:9]
	v_pk_fma_f32 v[8:9], v[132:133], s[28:29], v[0:1] op_sel_hi:[1,0,0]
	v_exp_f32_e32 v217, v15
	v_exp_f32_e32 v8, v8
	v_exp_f32_e32 v9, v9
	v_pk_fma_f32 v[14:15], v[138:139], s[28:29], v[0:1] op_sel_hi:[1,0,0]
	v_mul_f32_e32 v210, 0xbe16c740, v211
	v_exp_f32_e32 v218, v14
	v_pk_add_f32 v[12:13], v[8:9], v[10:11]
	v_pk_fma_f32 v[10:11], v[134:135], s[28:29], v[0:1] op_sel_hi:[1,0,0]
	v_exp_f32_e32 v219, v15
	v_exp_f32_e32 v10, v10
	v_exp_f32_e32 v11, v11
	v_pk_fma_f32 v[14:15], v[140:141], s[28:29], v[0:1] op_sel_hi:[1,0,0]
	s_add_i32 s14, s14, 1
	v_exp_f32_e32 v220, v14
	v_exp_f32_e32 v221, v15
	v_pk_fma_f32 v[14:15], v[142:143], s[28:29], v[0:1] op_sel_hi:[1,0,0]
	v_pk_add_f32 v[12:13], v[10:11], v[12:13]
	v_exp_f32_e32 v222, v14
	v_exp_f32_e32 v223, v15
	v_pk_fma_f32 v[14:15], v[112:113], s[28:29], v[0:1] op_sel_hi:[1,0,0]
	v_pk_add_f32 v[12:13], v[216:217], v[12:13]
	v_exp_f32_e32 v140, v14
	v_exp_f32_e32 v141, v15
	v_pk_fma_f32 v[14:15], v[114:115], s[28:29], v[0:1] op_sel_hi:[1,0,0]
	v_pk_add_f32 v[12:13], v[218:219], v[12:13]
	v_exp_f32_e32 v142, v14
	v_exp_f32_e32 v143, v15
	v_pk_fma_f32 v[14:15], v[116:117], s[28:29], v[0:1] op_sel_hi:[1,0,0]
	v_pk_add_f32 v[12:13], v[220:221], v[12:13]
	v_exp_f32_e32 v212, v14
	v_exp_f32_e32 v213, v15
	v_pk_fma_f32 v[14:15], v[118:119], s[28:29], v[0:1] op_sel_hi:[1,0,0]
	v_pk_add_f32 v[12:13], v[222:223], v[12:13]
	v_exp_f32_e32 v214, v14
	v_exp_f32_e32 v215, v15
	v_pk_fma_f32 v[14:15], v[120:121], s[28:29], v[0:1] op_sel_hi:[1,0,0]
	v_pk_add_f32 v[12:13], v[140:141], v[12:13]
	v_exp_f32_e32 v132, v14
	v_exp_f32_e32 v133, v15
	v_pk_fma_f32 v[14:15], v[122:123], s[28:29], v[0:1] op_sel_hi:[1,0,0]
	v_pk_add_f32 v[12:13], v[142:143], v[12:13]
	v_exp_f32_e32 v134, v14
	v_exp_f32_e32 v135, v15
	v_pk_fma_f32 v[14:15], v[124:125], s[28:29], v[0:1] op_sel_hi:[1,0,0]
	v_pk_add_f32 v[12:13], v[212:213], v[12:13]
	v_exp_f32_e32 v136, v14
	v_exp_f32_e32 v137, v15
	v_pk_fma_f32 v[14:15], v[126:127], s[28:29], v[0:1] op_sel_hi:[1,0,0]
	v_pk_add_f32 v[12:13], v[214:215], v[12:13]
	v_exp_f32_e32 v138, v14
	v_exp_f32_e32 v139, v15
	v_pk_add_f32 v[12:13], v[132:133], v[12:13]
	v_pk_fma_f32 v[14:15], v[98:99], s[28:29], v[210:211] op_sel_hi:[1,0,0]
	v_pk_add_f32 v[12:13], v[134:135], v[12:13]
	v_exp_f32_e32 v126, v14
	v_pk_add_f32 v[12:13], v[136:137], v[12:13]
	v_exp_f32_e32 v127, v15
	v_pk_add_f32 v[12:13], v[138:139], v[12:13]
	v_pk_fma_f32 v[14:15], v[100:101], s[28:29], v[210:211] op_sel_hi:[1,0,0]
	v_add_f32_e32 v1, v12, v13
	v_pk_fma_f32 v[12:13], v[96:97], s[28:29], v[210:211] op_sel_hi:[1,0,0]
	v_exp_f32_e32 v128, v14
	v_exp_f32_e32 v124, v12
	v_exp_f32_e32 v125, v13
	v_exp_f32_e32 v129, v15
	v_pk_fma_f32 v[14:15], v[102:103], s[28:29], v[210:211] op_sel_hi:[1,0,0]
	v_add_f32_e32 v241, v241, v1
	v_exp_f32_e32 v130, v14
	v_exp_f32_e32 v131, v15
	v_pk_fma_f32 v[14:15], v[104:105], s[28:29], v[210:211] op_sel_hi:[1,0,0]
	v_pk_add_f32 v[12:13], v[124:125], 0 op_sel_hi:[1,0]
	v_exp_f32_e32 v116, v14
	v_exp_f32_e32 v117, v15
	v_pk_fma_f32 v[14:15], v[106:107], s[28:29], v[210:211] op_sel_hi:[1,0,0]
	v_pk_add_f32 v[12:13], v[126:127], v[12:13]
	v_exp_f32_e32 v118, v14
	v_exp_f32_e32 v119, v15
	v_pk_fma_f32 v[14:15], v[108:109], s[28:29], v[210:211] op_sel_hi:[1,0,0]
	v_pk_add_f32 v[12:13], v[128:129], v[12:13]
	v_exp_f32_e32 v120, v14
	v_exp_f32_e32 v121, v15
	v_pk_fma_f32 v[14:15], v[110:111], s[28:29], v[210:211] op_sel_hi:[1,0,0]
	v_pk_add_f32 v[12:13], v[130:131], v[12:13]
	v_exp_f32_e32 v122, v14
	v_exp_f32_e32 v123, v15
	v_pk_fma_f32 v[14:15], v[80:81], s[28:29], v[210:211] op_sel_hi:[1,0,0]
	v_pk_add_f32 v[12:13], v[116:117], v[12:13]
	v_exp_f32_e32 v108, v14
	v_exp_f32_e32 v109, v15
	v_pk_fma_f32 v[14:15], v[82:83], s[28:29], v[210:211] op_sel_hi:[1,0,0]
	v_pk_add_f32 v[12:13], v[118:119], v[12:13]
	v_exp_f32_e32 v110, v14
	v_exp_f32_e32 v111, v15
	v_pk_fma_f32 v[14:15], v[84:85], s[28:29], v[210:211] op_sel_hi:[1,0,0]
	v_pk_add_f32 v[12:13], v[120:121], v[12:13]
	v_exp_f32_e32 v112, v14
	v_exp_f32_e32 v113, v15
	v_pk_fma_f32 v[14:15], v[86:87], s[28:29], v[210:211] op_sel_hi:[1,0,0]
	v_pk_add_f32 v[12:13], v[122:123], v[12:13]
	v_exp_f32_e32 v114, v14
	v_exp_f32_e32 v115, v15
	v_pk_fma_f32 v[14:15], v[88:89], s[28:29], v[210:211] op_sel_hi:[1,0,0]
	v_pk_add_f32 v[12:13], v[108:109], v[12:13]
	v_exp_f32_e32 v100, v14
	v_exp_f32_e32 v101, v15
	v_pk_fma_f32 v[14:15], v[90:91], s[28:29], v[210:211] op_sel_hi:[1,0,0]
	v_pk_add_f32 v[12:13], v[110:111], v[12:13]
	v_exp_f32_e32 v102, v14
	v_exp_f32_e32 v103, v15
	v_pk_fma_f32 v[14:15], v[92:93], s[28:29], v[210:211] op_sel_hi:[1,0,0]
	v_pk_add_f32 v[12:13], v[112:113], v[12:13]
	v_exp_f32_e32 v104, v14
	v_exp_f32_e32 v105, v15
	v_pk_fma_f32 v[14:15], v[94:95], s[28:29], v[210:211] op_sel_hi:[1,0,0]
	v_pk_add_f32 v[12:13], v[114:115], v[12:13]
	v_exp_f32_e32 v106, v14
	v_exp_f32_e32 v107, v15
	v_pk_add_f32 v[12:13], v[100:101], v[12:13]
	v_cvt_pk_bf16_f32 v14, v8, v9
	v_pk_add_f32 v[12:13], v[102:103], v[12:13]
	v_cvt_pk_bf16_f32 v15, v10, v11
	v_pk_add_f32 v[12:13], v[104:105], v[12:13]
	v_cvt_pk_bf16_f32 v124, v124, v125
	v_pk_add_f32 v[12:13], v[106:107], v[12:13]
	v_cvt_pk_bf16_f32 v125, v126, v127
	v_add_f32_e32 v1, v12, v13
	v_add_f32_e32 v240, v240, v1
	v_add3_u32 v1, s8, v238, v239
	v_cvt_pk_bf16_f32 v12, v4, v5
	v_cvt_pk_bf16_f32 v13, v6, v7
	ds_read_b64_tr_b16 v[8:9], v1 offset:13312
	ds_read_b64_tr_b16 v[10:11], v1 offset:14464
	ds_read_b64_tr_b16 v[4:5], v1 offset:13376
	ds_read_b64_tr_b16 v[6:7], v1 offset:14528
	v_cvt_pk_bf16_f32 v126, v128, v129
	v_cvt_pk_bf16_f32 v127, v130, v131
	s_waitcnt lgkmcnt(2)
; template <int DK, int DV, int MODE>
; DI void att_gload(const AttArgs& a, int tile, u32x4 (&kr)[(64 * (DK / 8) + NT - 1) / NT], u32x4 (&vr)[(64 * (DV / 8) + NT - 1) / NT]) {
;   constexpr int CK = DK / 8, CV = DV / 8;
;   constexpr int NKL = (64 * CK + NT - 1) / NT, NVL = (64 * CV + NT - 1) / NT;
;   const int t = tid_opaque();
;   const int kbase = tile * 64;
; #pragma unroll
;   for (int i = 0; i < NKL; ++i) {
;     const int id = min(t + NT * i, 64 * CK - 1);
;     const int row = id / CK, c = id % CK;
;     if constexpr (MODE == 3) {
;       const bf16_t* src = (c < 8) ? (a.k + (size_t)(kbase + row) * a.ldk + c * 8) : (a.k2 + (size_t)(kbase + row) * a.ldk2 + (c - 8) * 8);
;       kr[i] = *(const u32x4*)src;
;     } else {
;       kr[i] = *(const u32x4*)(a.k + (size_t)(kbase + row) * a.ldk + c * 8);
;     }
;   }
; #pragma unroll
;   for (int i = 0; i < NVL; ++i) {
;     const int id = t + NT * i;
;     const int row = id / CV, c = id % CV;
;     vr[i] = *(const u32x4*)(a.v + (size_t)(kbase + row) * a.ldv + c * 8);
;   }
; }
; template <int DK, int DV>
; DI void att_swrite(int buf, const u32x4 (&kr)[(64 * (DK / 8) + NT - 1) / NT], const u32x4 (&vr)[(64 * (DV / 8) + NT - 1) / NT]) {
;   constexpr int CK = DK / 8, CV = DV / 8;
;   constexpr int KST = DK * 2 + 16, VST = DV * 2 + 16;
;   constexpr int KBYTES = 64 * KST, VBYTES = 64 * VST, BUFB = KBYTES + VBYTES;
;   constexpr int NKL = (64 * CK + NT - 1) / NT, NVL = (64 * CV + NT - 1) / NT;
;   const int t = tid_opaque();
; #pragma unroll
;   for (int i = 0; i < NKL; ++i) {
;     const int id = t + NT * i;
;     const int row = id / CK, c = id % CK;
;     if (id < 64 * CK) *(u32x4*)(smem + buf * BUFB + row * KST + c * 16) = kr[i];
;   }
; #pragma unroll
;   for (int i = 0; i < NVL; ++i) {
;     const int id = t + NT * i;
;     const int row = id / CV, c = id % CV;
;     *(u32x4*)(smem + buf * BUFB + KBYTES + row * VST + c * 16) = vr[i];
;   }
; template <int DK, int DV, int MODE, int QB, bool PACK = false>
; DI void attn_item(const AttArgs& a, int q0, int t_lo, int t_hi) {
;     ...
;   for (int tile = t_lo; tile < t_hi; ++tile) {
;     const int buf = (tile - t_lo) & 1;
;     if (tile + 1 < t_hi) att_swrite<DK, DV>(buf ^ 1, kr, vr);
;     if (tile + 2 < t_hi) att_gload<DK, DV, MODE>(a, tile + 2, kr, vr);
;     const unsigned char* Kb = smem + buf * BUFB;
	v_mfma_f32_32x32x16_bf16 v[64:79], v[8:11], v[12:15], v[64:79]
	ds_read_b64_tr_b16 v[80:81], v1 offset:15616
	ds_read_b64_tr_b16 v[82:83], v1 offset:16768
	v_cvt_pk_bf16_f32 v84, v216, v217
	v_cvt_pk_bf16_f32 v85, v218, v219
	v_cvt_pk_bf16_f32 v86, v220, v221
	v_cvt_pk_bf16_f32 v87, v222, v223
	v_cvt_pk_bf16_f32 v92, v140, v141
	v_cvt_pk_bf16_f32 v93, v142, v143
	s_waitcnt lgkmcnt(2)
	v_mfma_f32_32x32x16_bf16 v[48:63], v[4:7], v[12:15], v[48:63]
	ds_read_b64_tr_b16 v[12:13], v1 offset:15680
	ds_read_b64_tr_b16 v[14:15], v1 offset:16832
	ds_read_b64_tr_b16 v[88:89], v1 offset:17920
	ds_read_b64_tr_b16 v[90:91], v1 offset:19072
	v_cvt_pk_bf16_f32 v94, v212, v213
	v_cvt_pk_bf16_f32 v95, v214, v215
	v_cvt_pk_bf16_f32 v132, v132, v133
	v_cvt_pk_bf16_f32 v133, v134, v135
	v_cvt_pk_bf16_f32 v134, v136, v137
	v_mfma_f32_32x32x16_bf16 v[32:47], v[8:11], v[124:127], v[32:47]
	v_cvt_pk_bf16_f32 v135, v138, v139
	s_add_u32 s6, s6, 0x20000
	s_addc_u32 s7, s7, 0
	s_cmp_eq_u32 s14, 31
	v_mfma_f32_32x32x16_bf16 v[16:31], v[4:7], v[124:127], v[16:31]
	v_cvt_pk_bf16_f32 v4, v116, v117
	v_cvt_pk_bf16_f32 v5, v118, v119
	v_cvt_pk_bf16_f32 v6, v120, v121
	v_cvt_pk_bf16_f32 v7, v122, v123
	s_waitcnt lgkmcnt(4)
	v_mfma_f32_32x32x16_bf16 v[64:79], v[80:83], v[84:87], v[64:79]
	s_waitcnt lgkmcnt(2)
	v_mfma_f32_32x32x16_bf16 v[48:63], v[12:15], v[84:87], v[48:63]
	ds_read_b64_tr_b16 v[84:85], v1 offset:17984
	ds_read_b64_tr_b16 v[86:87], v1 offset:19136
	ds_read_b64_tr_b16 v[96:97], v1 offset:20224
	ds_read_b64_tr_b16 v[98:99], v1 offset:21376
	v_mfma_f32_32x32x16_bf16 v[32:47], v[80:83], v[4:7], v[32:47]
	v_mfma_f32_32x32x16_bf16 v[16:31], v[12:15], v[4:7], v[16:31]
	v_cvt_pk_bf16_f32 v4, v108, v109
	v_cvt_pk_bf16_f32 v5, v110, v111
	v_cvt_pk_bf16_f32 v6, v112, v113
	v_cvt_pk_bf16_f32 v7, v114, v115
	s_waitcnt lgkmcnt(4)
	v_mfma_f32_32x32x16_bf16 v[64:79], v[88:91], v[92:95], v[64:79]
	s_waitcnt lgkmcnt(2)
	v_mfma_f32_32x32x16_bf16 v[48:63], v[84:87], v[92:95], v[48:63]
	ds_read_b64_tr_b16 v[92:93], v1 offset:20288
	ds_read_b64_tr_b16 v[94:95], v1 offset:21440
	s_waitcnt lgkmcnt(0)
	s_barrier
	v_mfma_f32_32x32x16_bf16 v[32:47], v[88:91], v[4:7], v[32:47]
	v_mfma_f32_32x32x16_bf16 v[16:31], v[84:87], v[4:7], v[16:31]
	v_cvt_pk_bf16_f32 v4, v100, v101
	v_cvt_pk_bf16_f32 v5, v102, v103
	v_cvt_pk_bf16_f32 v6, v104, v105
	v_cvt_pk_bf16_f32 v7, v106, v107
	v_mfma_f32_32x32x16_bf16 v[64:79], v[96:99], v[132:135], v[64:79]
	v_mfma_f32_32x32x16_bf16 v[48:63], v[92:95], v[132:135], v[48:63]
	v_mfma_f32_32x32x16_bf16 v[32:47], v[96:99], v[4:7], v[32:47]
	v_mfma_f32_32x32x16_bf16 v[16:31], v[92:95], v[4:7], v[16:31]
	s_cbranch_scc1 .LBB0_793
.LBB0_775:
	s_and_b32 s15, s14, 1
	s_xor_b32 s20, s15, 1
	s_mulk_i32 s20, 0x5800
	v_add_u32_e32 v0, s20, v248
	s_waitcnt vmcnt(2)
	ds_write_b128 v0, v[192:195]
	s_and_saveexec_b64 s[8:9], s[100:101]
	s_cbranch_execz .Lm3_nok2
	v_add_u32_e32 v0, s20, v249
	s_waitcnt vmcnt(1)
	ds_write_b128 v0, v[196:199]
.Lm3_nok2:
	s_or_b64 exec, exec, s[8:9]
	v_add_u32_e32 v0, s20, v250
	s_cmp_gt_u32 s14, 29
	s_waitcnt vmcnt(0)
	ds_write_b128 v0, v[200:203] offset:13312
	s_cbranch_scc1 .LBB0_789
	v_add_co_u32_e32 v226, vcc, v236, v226
	v_addc_co_u32_e32 v227, vcc, 0, v227, vcc
	v_add_co_u32_e32 v228, vcc, v237, v228
	v_addc_co_u32_e32 v229, vcc, 0, v229, vcc
	global_load_dwordx4 v[192:195], v[226:227], off
	global_load_dwordx4 v[196:199], v[228:229], off
	global_load_dwordx4 v[200:203], v251, s[6:7]
